# static priority raise (s_setprio 1) for waves 4-7 in the attention / HGRN pass A / pass C unit loops, reset at loop exit
# baseline (speedup 1.0000x reference)
.LBB0_114:
	s_and_b64 vcc, exec, s[6:7]
	s_cbranch_vccnz .LBB0_199
	s_movk_i32 s37, 0x90
	v_mul_lo_u32 v11, v76, s37
	v_readlane_b32 s11, v253, 3
	s_lshl_b32 s0, s28, 9
	v_readlane_b32 s6, v253, 5
	v_add_u32_e32 v60, s11, v11
	v_lshlrev_b32_e32 v11, 2, v56
	v_and_b32_e32 v56, 0x7c, v11
	s_add_i32 s0, s6, s0
	v_lshlrev_b32_e32 v11, 3, v55
	s_lshl_b32 s49, s28, 3
	v_and_b32_e32 v15, 64, v209
	v_add_u32_e32 v117, s0, v11
	s_ashr_i32 s0, s49, 31
	v_add_u32_e32 v118, s6, v11
	v_xor_b32_e32 v11, 16, v209
	v_add_u32_e32 v15, 64, v15
	v_writelane_b32 v254, s0, 39
	s_ashr_i32 s0, s12, 7
	v_cmp_lt_i32_e32 vcc, v11, v15
	s_cmpk_lt_u32 s12, 0x80
	v_readlane_b32 s8, v254, 8
	v_cndmask_b32_e32 v11, v209, v11, vcc
	s_cselect_b64 s[74:75], -1, 0
	s_cmp_eq_u32 s0, 1
	v_lshlrev_b32_e32 v119, 2, v11
	v_xor_b32_e32 v11, 32, v209
	v_mov_b32_e32 v51, v1
	v_readlane_b32 s9, v254, 9
	s_cselect_b64 s[6:7], -1, 0
	s_cmp_eq_u32 s0, 2
	v_cmp_lt_i32_e32 vcc, v11, v15
	v_lshl_add_u64 v[90:91], s[8:9], 0, v[50:51]
	s_cselect_b64 s[8:9], -1, 0
	s_add_i32 s10, s34, 1
	v_cndmask_b32_e32 v11, v209, v11, vcc
	s_and_b32 s35, s12, 0xffffffc0
	s_lshl_b32 s12, s28, 4
	v_readlane_b32 s13, v253, 2
	v_lshlrev_b32_e32 v120, 2, v11
	v_bitop3_b32 v11, s12, 64, v53 bitop3:0x36
	s_cmp_eq_u32 s28, 1
	v_lshl_add_u32 v59, v53, 2, s13
	v_readlane_b32 s14, v253, 4
	v_lshl_add_u32 v121, v11, 2, s13
	s_cselect_b64 s[12:13], -1, 0
	s_cmp_eq_u32 s28, 2
	v_add_u32_e32 v61, s14, v50
	s_mov_b64 s[16:17], s[90:91]
	v_add_u32_e32 v64, s14, v52
	s_cselect_b64 s[14:15], -1, 0
	s_cmp_eq_u32 s28, 3
	v_or_b32_e32 v63, s16, v53
	v_or_b32_e32 v92, s16, v54
	s_cselect_b64 s[16:17], -1, 0
	s_cmp_eq_u32 s28, 4
	s_cselect_b64 s[18:19], -1, 0
	s_cmp_eq_u32 s28, 5
	s_cselect_b64 s[20:21], -1, 0
	s_cmp_eq_u32 s28, 6
	s_cselect_b64 s[22:23], -1, 0
	s_cmp_eq_u32 s28, 7
	s_cselect_b64 s[24:25], -1, 0
	s_cmp_lt_i32 s0, 1
	s_cselect_b64 s[76:77], -1, 0
	s_cmp_lt_i32 s0, 2
	s_cselect_b64 s[78:79], -1, 0
	s_cmp_lt_i32 s0, 3
	s_cselect_b64 s[80:81], -1, 0
	s_cmp_lt_i32 s0, 4
	s_cselect_b64 s[82:83], -1, 0
	s_cmp_eq_u32 s34, 0
	s_cselect_b64 s[58:59], -1, 0
	s_cmp_lg_u32 s34, 0
	s_cselect_b64 s[62:63], -1, 0
	s_cmp_eq_u32 s34, 1
	v_ashrrev_i32_e32 v11, 31, v10
	s_cselect_b64 s[40:41], -1, 0
	s_cmp_gt_u32 s34, 1
	s_mul_i32 s10, s34, s10
	v_lshlrev_b64 v[100:101], 8, v[10:11]
	v_or_b32_e32 v11, 2, v54
	v_writelane_b32 v254, s40, 41
	s_cselect_b64 s[60:61], -1, 0
	s_cmp_eq_u32 s34, 2
	v_and_b32_e32 v88, 62, v58
	s_movk_i32 s38, 0x110
	v_lshl_add_u32 v58, s10, 3, v53
	v_cmp_gt_u32_e64 s[56:57], v11, v53
	v_or_b32_e32 v11, 3, v54
	v_writelane_b32 v254, s41, 42
	s_cselect_b64 s[40:41], -1, 0
	v_lshlrev_b32_e32 v116, 1, v55
	v_lshl_add_u32 v50, v55, 2, 0
	v_mad_u32_u24 v51, v78, s38, 0
	v_add_u32_e32 v62, 0, v52
	v_lshl_add_u32 v57, v57, 3, s11
	v_cmp_gt_u32_e64 s[10:11], 16, v55
	v_mul_lo_u32 v55, v12, s38
	v_mul_lo_u32 v65, v48, s38
	v_mul_lo_u32 v66, v14, s38
	v_mul_lo_u32 v67, v10, s38
	v_lshlrev_b64 v[94:95], 8, v[12:13]
	v_ashrrev_i32_e32 v49, 31, v48
	v_ashrrev_i32_e32 v15, 31, v14
	s_mul_i32 s36, s28, 0x880
	v_mul_u32_u24_e32 v10, 0x110, v58
	v_cmp_gt_u32_e64 s[52:53], v11, v53
	v_writelane_b32 v254, s40, 35
	s_cmp_eq_u32 s34, 3
	v_mul_lo_u32 v11, v63, s37
	v_mul_lo_u32 v12, v63, s38
	v_ashrrev_i32_e32 v77, 31, v76
	v_lshlrev_b64 v[96:97], 8, v[48:49]
	v_lshlrev_b64 v[98:99], 8, v[14:15]
	v_cmp_gt_u32_e64 s[54:55], v54, v53
	v_cmp_lt_u32_e64 s[28:29], v54, v53
	v_writelane_b32 v254, s41, 36
	s_cselect_b64 s[64:65], -1, 0
	v_ashrrev_i32_e32 v93, 31, v92
	v_add_u32_e32 v122, v60, v56
	v_add_u32_e32 v123, v61, v55
	v_add_u32_e32 v124, v61, v65
	v_add_u32_e32 v125, v61, v66
	v_add_u32_e32 v126, v61, v67
	v_add_u32_e32 v127, v64, v12
	v_add_u32_e32 v128, s35, v59
	v_add_u32_e32 v129, s36, v50
	v_add_u32_e32 v130, v51, v52
	v_add_u32_e32 v131, v62, v10
	v_add_u32_e32 v132, v57, v11
	v_readlane_b32 s47, v252, 10
	s_mov_b32 s69, s2
	s_waitcnt vmcnt(0)
	v_mov_b64_e32 v[102:103], v[86:87]
	v_mov_b64_e32 v[104:105], v[84:85]
	v_mov_b64_e32 v[106:107], v[82:83]
	v_mov_b64_e32 v[108:109], v[80:81]
	v_mov_b32_e32 v133, v75
	v_mov_b32_e32 v134, v147
	v_mov_b32_e32 v135, v146
	v_mov_b32_e32 v136, v145
	v_mov_b32_e32 v137, v144
	v_mov_b32_e32 v138, v143
	v_mov_b32_e32 v139, v142
	v_mov_b32_e32 v140, v141
	v_readfirstlane_b32 s0, v204
	s_cmp_lt_u32 s0, 0x100
	s_cbranch_scc1 .Lprio_hc
	s_setprio 1
.Lprio_hc:
	s_branch .LBB0_117

.LBB0_199:
	s_setprio 0
	s_mov_b64 s[6:7], 0
	s_mov_b32 s83, 0x800000

.LBB0_208:
	s_andn2_b64 vcc, exec, s[6:7]
	s_cbranch_vccnz .LBB0_232
	v_readlane_b32 s6, v252, 8
	s_waitcnt vmcnt(0)
	v_mov_b32_e32 v18, v204
	v_readlane_b32 s7, v252, 9
	s_andn2_b64 vcc, exec, s[6:7]
	v_readfirstlane_b32 s8, v18
	s_cbranch_vccnz .LBB0_232
	s_add_u32 s6, s30, 0xec00000
	s_addc_u32 s7, s31, 0
	s_add_u32 s10, s30, 0x16c00000
	s_addc_u32 s11, s31, 0
	s_ashr_i32 s22, s8, 6
	s_lshl_b32 s34, s22, 3
	s_ashr_i32 s35, s34, 31
	v_readlane_b32 s16, v252, 11
	s_add_u32 s12, s16, s34
	v_readlane_b32 s17, v252, 12
	v_readlane_b32 s0, v252, 13
	s_addc_u32 s13, s17, s35
	s_lshl_b32 s0, s0, 1
	v_and_b32_e32 v19, 63, v18
	s_add_u32 s14, s10, s0
	s_addc_u32 s15, s11, 0
	v_lshlrev_b32_e32 v0, 2, v19
	v_lshl_add_u64 v[2:3], s[14:15], 0, v[0:1]
	s_lshl_b64 s[12:13], s[12:13], 11
	v_lshl_add_u64 v[2:3], v[2:3], 0, s[12:13]
	s_movk_i32 s9, 0x1000
	v_add_co_u32_e32 v4, vcc, s9, v2
	s_movk_i32 s9, 0x2000
	s_nop 0
	v_addc_co_u32_e32 v5, vcc, 0, v3, vcc
	v_add_co_u32_e32 v6, vcc, s9, v2
	s_movk_i32 s9, 0x3000
	s_nop 0
	v_addc_co_u32_e32 v7, vcc, 0, v3, vcc
	global_load_dword v58, v[6:7], off offset:-4096
	global_load_dword v60, v[6:7], off
	global_load_dword v61, v[6:7], off offset:2048
	v_add_co_u32_e32 v6, vcc, s9, v2
	s_movk_i32 s12, 0x90
	s_nop 0
	v_addc_co_u32_e32 v7, vcc, 0, v3, vcc
	global_load_dword v62, v[2:3], off
	global_load_dword v63, v[2:3], off offset:2048
	global_load_dword v64, v[4:5], off offset:2048
	global_load_dword v65, v[6:7], off
	global_load_dword v66, v[6:7], off offset:2048
	v_lshlrev_b32_e32 v2, 1, v18
	v_and_b32_e32 v10, 62, v2
	v_or_b32_e32 v2, s16, v10
	v_mov_b32_e32 v3, s17
	v_ashrrev_i32_e32 v4, 2, v18
	v_lshlrev_b64 v[2:3], 11, v[2:3]
	v_and_b32_e32 v12, -8, v4
	v_lshl_add_u64 v[2:3], s[6:7], 0, v[2:3]
	v_ashrrev_i32_e32 v13, 31, v12
	v_lshl_add_u64 v[2:3], v[2:3], 0, s[0:1]
	v_lshl_add_u64 v[6:7], v[12:13], 1, v[2:3]
	global_load_dwordx4 v[2:5], v[6:7], off
	s_nop 0
	global_load_dwordx4 v[6:9], v[6:7], off offset:2048
	s_lshl_b32 s0, s22, 9
	s_add_i32 s0, s0, 0
	v_mul_lo_u32 v11, v12, s12
	s_cmp_gt_u32 s8, 63
	v_and_b32_e32 v20, 15, v18
	v_add_u32_e32 v21, 0, v11
	v_lshlrev_b32_e32 v11, 2, v18
	v_lshlrev_b32_e32 v16, 3, v19
	s_cselect_b64 s[8:9], -1, 0
	v_mov_b32_e32 v17, v1
	s_lshl_b32 s24, s22, 4
	v_and_b32_e32 v22, 0x7c, v11
	v_add_u32_e32 v11, s0, v16
	v_lshl_add_u64 v[14:15], s[10:11], 0, v[0:1]
	v_add_u32_e32 v59, 0, v16
	v_lshl_add_u64 v[16:17], s[30:31], 0, v[16:17]
	s_mov_b64 s[10:11], 0x1ec00000
	s_ashr_i32 s25, s24, 31
	v_or_b32_e32 v0, s24, v20
	v_lshl_add_u64 v[16:17], v[16:17], 0, s[10:11]
	v_mul_lo_u32 v0, v0, s12
	s_lshl_b64 s[10:11], s[24:25], 1
	v_readlane_b32 s12, v254, 8
	v_readlane_b32 s13, v254, 9
	s_add_u32 s10, s12, s10
	v_add_u32_e32 v24, 0, v0
	s_addc_u32 s11, s13, s11
	v_lshrrev_b32_e32 v0, 1, v18
	s_movk_i32 s0, 0x118
	v_and_b32_e32 v0, 24, v0
	s_cmp_lt_i32 s22, 1
	v_mad_u32_u24 v23, v19, s0, v59
	v_and_b32_e32 v25, 48, v18
	v_lshl_add_u64 v[18:19], s[10:11], 0, v[0:1]
	s_cselect_b64 s[10:11], -1, 0
	s_cmp_lt_i32 s22, 2
	s_cselect_b64 s[12:13], -1, 0
	s_cmp_lt_i32 s22, 3
	s_cselect_b64 s[14:15], -1, 0
	s_cmp_lt_i32 s22, 4
	s_cselect_b64 s[16:17], -1, 0
	s_cmp_lt_i32 s22, 5
	s_cselect_b64 s[18:19], -1, 0
	s_cmp_lt_i32 s22, 6
	v_add_u32_e32 v26, 0, v25
	s_cselect_b64 s[20:21], -1, 0
	s_cmp_lt_i32 s22, 7
	v_mul_u32_u24_e32 v27, 0x90, v20
	v_lshlrev_b32_e32 v0, 8, v20
	s_cselect_b64 s[22:23], -1, 0
	v_lshl_add_u64 v[18:19], v[18:19], 0, v[0:1]
	v_add_u32_e32 v67, v21, v22
	v_add_u32_e32 v68, s24, v23
	v_add_u32_e32 v69, v24, v25
	v_add_u32_e32 v70, v26, v27
	v_readlane_b32 s38, v252, 10
	s_mov_b32 s28, s2
	v_readfirstlane_b32 s0, v204
	s_cmp_lt_u32 s0, 0x100
	s_cbranch_scc1 .Lprio_ha
	s_setprio 1

.LBB0_232:
	s_setprio 0
	s_mov_b64 s[6:7], 0

.LBB0_313:
	s_and_b64 vcc, exec, s[8:9]
	s_cbranch_vccnz .LBB0_438
	v_and_b32_e32 v3, 64, v209
	v_xor_b32_e32 v2, 1, v209
	v_add_u32_e32 v3, 64, v3
	v_cmp_lt_i32_e32 vcc, v2, v3
	v_lshlrev_b32_e32 v0, 2, v73
	v_readlane_b32 s58, v253, 8
	v_cndmask_b32_e32 v2, v209, v2, vcc
	v_lshlrev_b32_e32 v174, 2, v2
	v_xor_b32_e32 v2, 2, v209
	v_cmp_lt_i32_e32 vcc, v2, v3
	v_readlane_b32 s12, v253, 23
	v_add_u32_e32 v173, s58, v0
	v_cndmask_b32_e32 v2, v209, v2, vcc
	v_lshlrev_b32_e32 v175, 2, v2
	v_xor_b32_e32 v2, 4, v209
	v_and_b32_e32 v0, 0x1fc, v0
	s_and_b64 s[8:9], s[92:93], exec
	v_readlane_b32 s13, v253, 24
	v_cmp_lt_i32_e32 vcc, v2, v3
	v_add_u32_e32 v69, 0, v0
	v_xor_b32_e32 v0, 16, v209
	s_cselect_b32 s0, 5, 3
	s_and_b64 s[8:9], s[12:13], exec
	v_cndmask_b32_e32 v2, v209, v2, vcc
	v_cmp_lt_i32_e32 vcc, v0, v3
	s_cselect_b32 s47, 7, s0
	s_add_i32 s56, s56, -1
	s_lshl_b32 s24, s28, 4
	v_cndmask_b32_e32 v0, v209, v0, vcc
	s_and_b64 s[8:9], s[92:93], exec
	v_lshlrev_b32_e32 v177, 2, v0
	v_xor_b32_e32 v0, 32, v209
	s_cselect_b32 s0, 2, 4
	s_and_b64 s[8:9], s[12:13], exec
	v_cmp_lt_i32_e32 vcc, v0, v3
	v_add_u32_e32 v3, 0x400, v73
	s_cselect_b32 s57, 0, s0
	v_cndmask_b32_e32 v0, v209, v0, vcc
	s_and_b64 s[8:9], s[92:93], exec
	v_ashrrev_i32_e32 v180, 3, v3
	v_add_u32_e32 v3, 0x600, v73
	v_lshlrev_b32_e32 v178, 2, v0
	s_cselect_b32 s0, 12, 10
	s_and_b64 s[8:9], s[12:13], exec
	v_add_u32_e32 v0, 0x200, v73
	v_ashrrev_i32_e32 v181, 3, v3
	v_lshlrev_b32_e32 v3, 1, v73
	s_cselect_b32 s99, 14, s0
	v_ashrrev_i32_e32 v179, 3, v0
	v_and_b32_e32 v182, 0xfe, v3
	v_ashrrev_i32_e32 v3, 4, v73
	v_ashrrev_i32_e32 v0, 4, v0
	s_ashr_i32 s0, s24, 31
	v_and_b32_e32 v124, -8, v3
	v_and_b32_e32 v126, -8, v0
	v_mov_b32_e32 v121, s0
	s_movk_i32 s0, 0x210
	v_lshlrev_b32_e32 v128, 2, v74
	v_mul_lo_u32 v78, v124, s0
	v_mul_lo_u32 v79, v126, s0
	s_add_i32 s29, s28, 2
	s_add_i32 s35, s28, 4
	s_add_i32 s34, s28, 6
	s_add_i32 s0, s28, 8
	v_mov_b32_e32 v71, v1
	v_sub_u32_e32 v0, v72, v128
	s_add_i32 s40, s24, 16
	s_lshl_b32 s41, s29, 4
	s_add_i32 s42, s24, 48
	s_lshl_b32 s43, s35, 4
	s_add_i32 s49, s24, 0x50
	s_lshl_b32 s52, s34, 4
	s_add_i32 s48, s24, 0x70
	s_lshl_b32 s53, s0, 4
	v_or_b32_e32 v120, s24, v72
	v_lshl_add_u64 v[122:123], s[10:11], 0, v[70:71]
	v_add_u32_e32 v70, 0x80, v0
	s_movk_i32 s8, 0x90
	v_or_b32_e32 v81, s40, v72
	v_or_b32_e32 v82, s41, v72
	v_or_b32_e32 v83, s42, v72
	v_or_b32_e32 v84, s43, v72
	v_or_b32_e32 v85, s49, v72
	v_or_b32_e32 v86, s52, v72
	v_or_b32_e32 v87, s48, v72
	v_or_b32_e32 v88, s53, v72
	s_movk_i32 s55, 0x81
	v_lshl_add_u32 v3, v74, 4, 0
	v_cmp_eq_u32_e32 vcc, 0, v74
	v_mul_lo_u32 v74, v129, s8
	v_mul_lo_u32 v75, v179, s8
	v_mul_lo_u32 v76, v180, s8
	v_mul_lo_u32 v77, v181, s8
	v_mul_lo_u32 v80, v120, s8
	v_mul_lo_u32 v81, v81, s8
	v_mul_lo_u32 v82, v82, s8
	v_mul_lo_u32 v83, v83, s8
	v_mul_lo_u32 v84, v84, s8
	v_mul_lo_u32 v85, v85, s8
	v_mul_lo_u32 v86, v86, s8
	v_mul_lo_u32 v87, v87, s8
	v_mul_lo_u32 v88, v88, s8
	v_cmp_gt_u32_e64 s[8:9], s55, v70
	v_lshl_add_u32 v183, v70, 2, s58
	v_add_u32_e32 v70, 0x7f, v0
	v_cmp_gt_u32_e64 s[10:11], s55, v70
	v_lshl_add_u32 v184, v70, 2, s58
	v_add_u32_e32 v70, 0x7e, v0
	v_cmp_gt_u32_e64 s[12:13], s55, v70
	v_lshl_add_u32 v185, v70, 2, s58
	v_add_u32_e32 v70, 0x7d, v0
	v_lshl_add_u32 v187, v0, 2, s58
	v_cmp_lt_i32_e64 s[16:17], -1, v0
	v_cmp_lt_i32_e64 s[18:19], 0, v0
	v_cmp_lt_i32_e64 s[20:21], 1, v0
	v_cmp_lt_i32_e64 s[22:23], 2, v0
	v_or_b32_e32 v0, s24, v128
	s_movk_i32 s54, 0x7f
	s_and_b64 s[38:39], s[88:89], vcc
	v_cmp_gt_u32_e64 s[14:15], s55, v70
	v_lshl_add_u32 v186, v70, 2, s58
	v_cmp_lt_i32_e32 vcc, s54, v0
	v_or_b32_e32 v70, 1, v128
	s_and_b64 s[24:25], s[8:9], vcc
	v_sub_u32_e32 v89, v72, v70
	v_writelane_b32 v254, s24, 39
	v_add_u32_e32 v90, 0x80, v89
	s_movk_i32 s59, 0x7e
	v_lshl_add_u32 v191, v89, 2, s58
	v_or_b32_e32 v89, 2, v128
	v_writelane_b32 v254, s25, 40
	v_cmp_gt_u32_e32 vcc, s55, v90
	v_cmp_lt_i32_e64 s[24:25], s59, v0
	v_sub_u32_e32 v90, v72, v89
	s_and_b64 s[24:25], vcc, s[24:25]
	v_add_u32_e32 v91, 0x80, v90
	v_writelane_b32 v254, s24, 41
	v_cmp_gt_u32_e32 vcc, s55, v91
	v_or_b32_e32 v91, 2, v0
	v_writelane_b32 v254, s25, 42
	v_cmp_lt_i32_e64 s[24:25], s54, v91
	v_lshl_add_u32 v192, v90, 2, s58
	v_or_b32_e32 v90, 3, v128
	s_and_b64 s[24:25], vcc, s[24:25]
	v_sub_u32_e32 v91, v72, v90
	v_writelane_b32 v254, s24, 35
	v_add_u32_e32 v92, 0x80, v91
	v_or_b32_e32 v0, 3, v0
	v_writelane_b32 v254, s25, 36
	v_cmp_gt_u32_e32 vcc, s55, v92
	v_cmp_lt_i32_e64 s[24:25], s54, v0
	s_and_b64 s[24:25], vcc, s[24:25]
	v_or_b32_e32 v0, s40, v128
	v_writelane_b32 v254, s24, 25
	v_lshlrev_b32_e32 v176, 2, v2
	v_lshlrev_b32_e32 v2, 4, v73
	v_writelane_b32 v254, s25, 26
	v_or_b32_e32 v73, -16, v73
	v_cmp_lt_i32_e64 s[24:25], s54, v0
	v_lshl_add_u32 v193, v91, 2, s58
	v_sub_u32_e32 v91, v73, v128
	v_writelane_b32 v254, s24, 33
	v_lshl_add_u32 v194, v91, 2, s58
	v_sub_u32_e32 v91, v73, v70
	v_writelane_b32 v254, s25, 34
	v_cmp_lt_i32_e64 s[24:25], s59, v0
	v_lshl_add_u32 v195, v91, 2, s58
	v_or_b32_e32 v91, 2, v0
	v_writelane_b32 v254, s24, 27
	v_or_b32_e32 v0, 3, v0
	v_or_b32_e32 v93, 0xffffff80, v72
	v_writelane_b32 v254, s25, 28
	v_cmp_lt_i32_e64 s[24:25], s54, v91
	v_sub_u32_e32 v91, v73, v89
	v_lshl_add_u32 v196, v91, 2, s58
	v_writelane_b32 v254, s24, 43
	v_sub_u32_e32 v94, v93, v128
	v_add_u32_e32 v95, 0x80, v94
	v_writelane_b32 v254, s25, 44
	v_cmp_lt_i32_e64 s[24:25], s54, v0
	v_sub_u32_e32 v0, v73, v90
	v_lshl_add_u32 v197, v0, 2, s58
	v_writelane_b32 v254, s24, 37
	v_or_b32_e32 v0, s41, v128
	v_or_b32_e32 v73, 0xffffffe0, v72
	v_writelane_b32 v254, s25, 38
	v_cmp_lt_i32_e64 s[24:25], s54, v0
	v_sub_u32_e32 v91, v73, v128
	v_lshl_add_u32 v198, v91, 2, s58
	v_writelane_b32 v254, s24, 29
	v_sub_u32_e32 v91, v73, v70
	v_lshl_add_u32 v200, v91, 2, s58
	v_writelane_b32 v254, s25, 30
	v_cmp_lt_i32_e64 s[24:25], s59, v0
	v_or_b32_e32 v91, 2, v0
	v_or_b32_e32 v0, 3, v0
	v_writelane_b32 v254, s24, 31
	v_or_b32_e32 v92, s53, v128
	v_cmp_gt_u32_e32 vcc, s55, v95
	v_writelane_b32 v254, s25, 32
	v_cmp_lt_i32_e64 s[24:25], s54, v91
	v_sub_u32_e32 v91, v73, v89
	v_lshl_add_u32 v201, v91, 2, s58
	v_writelane_b32 v254, s24, 45
	v_sub_u32_e32 v95, v93, v70
	v_cmp_lt_i32_e64 s[64:65], s54, v92
	v_writelane_b32 v254, s25, 46
	v_cmp_lt_i32_e64 s[24:25], s54, v0
	v_sub_u32_e32 v0, v73, v90
	v_lshl_add_u32 v202, v0, 2, s58
	v_writelane_b32 v254, s24, 47
	v_or_b32_e32 v0, s42, v128
	v_or_b32_e32 v73, 0xffffffd0, v72
	v_writelane_b32 v254, s25, 48
	v_cmp_lt_i32_e64 s[24:25], s54, v0
	v_sub_u32_e32 v91, v73, v128
	v_lshl_add_u32 v203, v91, 2, s58
	v_writelane_b32 v254, s24, 49
	v_sub_u32_e32 v91, v73, v70
	v_lshl_add_u32 v210, v91, 2, s58
	v_writelane_b32 v254, s25, 50
	v_cmp_lt_i32_e64 s[24:25], s59, v0
	v_or_b32_e32 v91, 2, v0
	v_or_b32_e32 v0, 3, v0
	v_writelane_b32 v254, s24, 51
	v_add_u32_e32 v96, 0x80, v95
	s_and_b64 s[40:41], vcc, s[64:65]
	v_writelane_b32 v254, s25, 52
	v_cmp_lt_i32_e64 s[24:25], s54, v91
	v_sub_u32_e32 v91, v73, v89
	v_lshl_add_u32 v211, v91, 2, s58
	v_writelane_b32 v254, s24, 53
	v_cmp_gt_u32_e32 vcc, s55, v96
	v_sub_u32_e32 v96, v93, v89
	v_writelane_b32 v254, s25, 54
	v_cmp_lt_i32_e64 s[24:25], s54, v0
	v_sub_u32_e32 v0, v73, v90
	v_lshl_add_u32 v212, v0, 2, s58
	v_writelane_b32 v254, s24, 55
	v_or_b32_e32 v0, s43, v128
	v_or_b32_e32 v73, 0xffffffc0, v72
	v_writelane_b32 v254, s25, 56
	v_cmp_lt_i32_e64 s[24:25], s54, v0
	v_sub_u32_e32 v91, v73, v128
	v_lshl_add_u32 v213, v91, 2, s58
	v_writelane_b32 v254, s24, 57
	v_sub_u32_e32 v91, v73, v70
	v_lshl_add_u32 v214, v91, 2, s58
	v_writelane_b32 v254, s25, 58
	v_cmp_lt_i32_e64 s[24:25], s59, v0
	v_or_b32_e32 v91, 2, v0
	v_or_b32_e32 v0, 3, v0
	v_writelane_b32 v254, s24, 59
	v_cmp_lt_i32_e64 s[64:65], s59, v92
	v_add_u32_e32 v97, 0x80, v96
	v_writelane_b32 v254, s25, 60
	v_cmp_lt_i32_e64 s[24:25], s54, v91
	v_sub_u32_e32 v91, v73, v89
	v_lshl_add_u32 v215, v91, 2, s58
	v_writelane_b32 v254, s24, 61
	s_and_b64 s[42:43], vcc, s[64:65]
	v_cmp_gt_u32_e32 vcc, s55, v97
	v_writelane_b32 v254, s25, 62
	v_cmp_lt_i32_e64 s[24:25], s54, v0
	v_sub_u32_e32 v0, v73, v90
	v_or_b32_e32 v73, 0xffffffb0, v72
	v_sub_u32_e32 v91, v73, v128
	v_or_b32_e32 v97, 2, v92
	v_sub_u32_e32 v93, v93, v90
	v_writelane_b32 v254, s24, 63
	v_lshl_add_u32 v216, v0, 2, s58
	v_or_b32_e32 v0, s49, v128
	v_lshl_add_u32 v217, v91, 2, s58
	v_sub_u32_e32 v91, v73, v70
	v_cmp_lt_i32_e64 s[64:65], s54, v97
	v_add_u32_e32 v97, 0x80, v93
	v_or_b32_e32 v92, 3, v92
	v_writelane_b32 v255, s25, 0
	v_cmp_lt_i32_e64 s[24:25], s54, v0
	v_cmp_lt_i32_e64 s[60:61], s59, v0
	v_lshl_add_u32 v218, v91, 2, s58
	v_or_b32_e32 v91, 2, v0
	v_or_b32_e32 v0, 3, v0
	s_and_b64 s[88:89], vcc, s[64:65]
	v_cmp_gt_u32_e32 vcc, s55, v97
	v_cmp_lt_i32_e64 s[64:65], s54, v92
	s_and_b64 s[92:93], vcc, s[64:65]
	v_cmp_lt_i32_e64 s[64:65], s54, v0
	v_sub_u32_e32 v0, v73, v90
	v_cmp_lt_i32_e64 s[62:63], s54, v91
	v_sub_u32_e32 v91, v73, v89
	v_lshl_add_u32 v220, v0, 2, s58
	v_or_b32_e32 v0, 0xffffffa0, v72
	v_lshl_add_u32 v219, v91, 2, s58
	v_or_b32_e32 v91, s52, v128
	v_sub_u32_e32 v99, v0, v70
	v_lshl_add_u32 v222, v99, 2, s58
	v_or_b32_e32 v99, 2, v91
	v_sub_u32_e32 v97, v0, v128
	v_cmp_lt_i32_e64 s[70:71], s54, v99
	v_sub_u32_e32 v99, v0, v89
	v_sub_u32_e32 v0, v0, v90
	v_writelane_b32 v255, s24, 1
	v_lshl_add_u32 v224, v0, 2, s58
	v_or_b32_e32 v0, 0xffffff90, v72
	v_and_b32_e32 v2, 0x70, v2
	v_sub_u32_e32 v71, v3, v68
	v_writelane_b32 v255, s25, 2
	v_or_b32_e32 v73, s48, v128
	v_lshl_add_u32 v223, v99, 2, s58
	v_sub_u32_e32 v99, v0, v128
	v_sub_u32_e32 v70, v0, v70
	v_sub_u32_e32 v89, v0, v89
	v_sub_u32_e32 v0, v0, v90
	v_readlane_b32 s24, v254, 12
	v_add_u32_e32 v2, 0, v2
	v_lshl_add_u32 v92, s28, 5, v71
	v_cmp_lt_i32_e64 s[66:67], s54, v91
	v_lshl_add_u32 v221, v97, 2, s58
	v_lshl_add_u32 v97, s29, 5, v71
	v_lshl_add_u32 v98, s35, 5, v71
	v_cmp_lt_i32_e64 s[68:69], s59, v91
	v_lshl_add_u32 v100, s34, 5, v71
	v_lshl_add_u32 v71, s0, 5, v71
	v_or_b32_e32 v91, 3, v91
	v_lshl_add_u32 v226, v70, 2, s58
	v_or_b32_e32 v70, 2, v73
	v_lshl_add_u32 v227, v89, 2, s58
	v_or_b32_e32 v89, 3, v73
	v_lshl_add_u32 v228, v0, 2, s58
	v_mul_u32_u24_e32 v72, 0x210, v72
	v_lshlrev_b32_e32 v0, 1, v68
	v_readlane_b32 s25, v254, 13
	v_ashrrev_i32_e32 v125, 31, v124
	v_ashrrev_i32_e32 v127, 31, v126
	v_add_u32_e32 v188, -4, v187
	v_add_u32_e32 v189, -8, v187
	v_add_u32_e32 v190, -12, v187
	v_lshl_add_u32 v225, v99, 2, s58
	v_lshl_add_u32 v229, v94, 2, s58
	v_lshl_add_u32 v230, v95, 2, s58
	v_lshl_add_u32 v231, v96, 2, s58
	v_lshl_add_u32 v232, v93, 2, s58
	v_lshl_add_u64 v[132:133], s[24:25], 0, v[0:1]
	v_add_u32_e32 v233, v2, v74
	v_add_u32_e32 v234, v2, v75
	v_add_u32_e32 v235, v2, v76
	v_add_u32_e32 v236, v2, v77
	v_add_u32_e32 v237, v69, v78
	v_add_u32_e32 v238, v69, v79
	v_add_u32_e32 v239, v3, v80
	v_add_u32_e32 v240, v3, v81
	v_add_u32_e32 v241, v3, v82
	v_add_u32_e32 v242, v3, v83
	v_add_u32_e32 v243, v3, v84
	v_add_u32_e32 v244, v3, v85
	v_add_u32_e32 v245, v3, v86
	v_add_u32_e32 v246, v3, v87
	v_add_u32_e32 v247, v3, v88
	v_add_u32_e32 v248, v92, v72
	v_add_u32_e32 v249, v97, v72
	v_add_u32_e32 v250, v98, v72
	v_add_u32_e32 v251, v100, v72
	v_add_u32_e32 v206, v71, v72
	v_readlane_b32 s58, v252, 47
	v_cmp_lt_i32_e64 s[72:73], s54, v91
	v_cmp_lt_i32_e64 s[74:75], s54, v73
	v_cmp_lt_i32_e64 s[76:77], s59, v73
	v_cmp_lt_i32_e64 s[78:79], s54, v70
	v_cmp_lt_i32_e64 s[80:81], s54, v89
	v_readfirstlane_b32 s24, v204
	s_cmp_lt_u32 s24, 0x100
	s_cbranch_scc1 .Lprio_att
	s_setprio 1
